# SB attention: next key block K rows prefetched one iteration ahead, out-norm gains hoisted out of the task loop, next task id fetched early
# baseline (speedup 1.0000x reference)
.LBB0_836:
	v_readlane_b32 s35, v253, 32
	s_lshl_b32 s44, s35, 6
	s_waitcnt vmcnt(0)
	v_mov_b32_e32 v2, v179
	s_lshl_b64 s[22:23], s[44:45], 2
	v_readlane_b32 s0, v251, 38
	s_add_u32 s40, s0, s22
	v_readlane_b32 s0, v251, 39
	v_bfe_u32 v1, v2, 4, 2
	v_readlane_b32 s10, v250, 59
	v_readlane_b32 s48, v249, 8
	v_and_b32_e32 v0, 63, v2
	s_addc_u32 s41, s0, s23
	v_and_b32_e32 v32, 15, v2
	v_lshlrev_b32_e32 v34, 3, v1
	v_mov_b32_e32 v35, v157
	v_readlane_b32 s11, v250, 60
	v_readlane_b32 s52, v249, 12
	v_cmp_eq_u32_e64 s[0:1], 0, v0
	v_lshlrev_b32_e32 v36, 2, v1
	v_cmp_eq_u32_e64 s[4:5], 3, v1
	v_cmp_gt_u32_e64 s[6:7], 32, v0
	v_cmp_gt_u32_e64 s[8:9], 16, v0
	v_lshlrev_b32_e32 v156, 12, v32
	v_lshl_add_u64 v[0:1], s[10:11], 0, v[34:35]
	v_readlane_b32 s49, v249, 9
	v_readlane_b32 s50, v249, 10
	v_readlane_b32 s51, v249, 11
	v_readlane_b32 s53, v249, 13
	v_readlane_b32 s56, v249, 16
	v_readlane_b32 s57, v249, 17
	v_readlane_b32 s60, v249, 20
	v_readlane_b32 s61, v249, 21
	s_add_u32 s10, s52, s22
	v_lshl_add_u64 v[38:39], v[0:1], 0, v[156:157]
	v_readlane_b32 s54, v249, 14
	v_readlane_b32 s55, v249, 15
	v_readlane_b32 s62, v249, 22
	s_addc_u32 s11, s53, s23
	v_and_b32_e32 v156, 48, v2
	v_readlane_b32 s60, v253, 17
	v_readlane_b32 s88, v253, 19
	v_readlane_b32 s50, v253, 21
	v_readlane_b32 s48, v253, 23
	v_readlane_b32 s52, v253, 25
	v_readlane_b32 s56, v249, 51
	v_readlane_b32 s70, v253, 37
	v_readlane_b32 s74, v253, 35
	v_readlane_b32 s94, v253, 33
	v_lshl_add_u64 v[40:41], s[10:11], 0, v[156:157]
	v_readlane_b32 s61, v253, 18
	v_readlane_b32 s89, v253, 20
	v_readlane_b32 s51, v253, 22
	v_readlane_b32 s49, v253, 24
	v_readlane_b32 s53, v253, 26
	v_readlane_b32 s57, v249, 52
	v_readlane_b32 s62, v253, 27
	s_mov_b64 s[54:55], 0x1200
	v_readlane_b32 s71, v253, 38
	v_readlane_b32 s75, v253, 36
	v_readlane_b32 s95, v253, 34
	v_readlane_b32 s58, v249, 18
	v_readlane_b32 s59, v249, 19
	v_readlane_b32 s63, v249, 23
	global_load_dwordx4 v[64:67], v[40:41], off
	global_load_dwordx4 v[68:71], v[40:41], off offset:64
	global_load_dwordx4 v[72:75], v[40:41], off offset:128
	global_load_dwordx4 v[76:79], v[40:41], off offset:192
	s_mov_b64 s[10:11], exec
	s_mov_b64 exec, s[0:1]
	v_mov_b32_e32 v81, 1
	global_atomic_add v81, v157, v81, s[40:41] sc0
	s_mov_b64 exec, s[10:11]
	s_branch .LBB0_838

.LBB0_838:
	s_waitcnt vmcnt(0)
	v_readfirstlane_b32 s12, v81
	s_cmpk_gt_i32 s12, 0xfff
	s_mov_b64 s[10:11], -1
	s_cbranch_scc1 .LBB0_837
	s_mov_b64 s[14:15], exec
	s_mov_b64 exec, s[0:1]
	v_mov_b32_e32 v81, 1
	global_atomic_add v81, v157, v81, s[40:41] sc0
	s_mov_b64 exec, s[14:15]
	s_ashr_i32 s14, s12, 9
	s_lshl_b32 s16, s12, 4
	s_and_b32 s11, s16, 0x7f0
	s_ashr_i32 s15, s14, 31
	s_ashr_i32 s10, s12, 7
	s_lshl_b64 s[12:13], s[14:15], 11
	v_or_b32_e32 v33, s11, v32
	v_or_b32_e32 v42, s12, v33
	v_mov_b64_e32 v[0:1], s[20:21]
	s_lshl_b32 s11, s10, 6
	v_mad_u64_u32 v[0:1], s[14:15], v42, s90, v[0:1]
	s_and_b32 s46, s11, 0xc0
	v_mad_i32_i24 v1, s13, v222, v1
	s_lshl_b32 s44, s46, 1
	v_lshl_add_u64 v[0:1], v[0:1], 0, s[44:45]
	v_lshlrev_b32_e32 v156, 1, v34
	v_lshl_add_u64 v[0:1], v[0:1], 0, v[156:157]
	global_load_dwordx4 v[16:19], v[0:1], off
	global_load_dwordx4 v[20:23], v[0:1], off offset:64
	v_and_b32_e32 v0, 63, v217
	v_cmp_gt_u32_e32 vcc, 48, v0
	s_ashr_i32 s11, s10, 31
	s_lshl_b64 s[10:11], s[10:11], 18
	v_cndmask_b32_e64 v1, 0, 16, vcc
	v_cmp_gt_u32_e32 vcc, 16, v0
	v_mov_b32_e32 v28, 0
	v_mov_b32_e32 v43, s13
	v_cndmask_b32_e64 v0, 0, 48, vcc
	v_add_lshl_u32 v50, v0, v217, 2
	v_and_or_b32 v0, v217, 64, v32
	v_mov_b32_e32 v45, s13
	v_or_b32_e32 v44, s12, v32
	v_add_lshl_u32 v35, v1, v217, 2
	v_lshl_or_b32 v37, v217, 2, v223
	v_lshlrev_b32_e32 v51, 2, v0
	v_lshl_add_u64 v[46:47], v[38:39], 0, s[10:11]
	s_and_b32 s58, s16, 0x7e0
	v_mov_b32_e32 v0, 0
	v_mov_b32_e32 v1, v28
	v_mov_b32_e32 v2, v28
	v_mov_b32_e32 v3, v28
	v_mov_b32_e32 v4, 0
	v_mov_b32_e32 v5, v28
	v_mov_b32_e32 v6, v28
	v_mov_b32_e32 v7, v28
	v_mov_b32_e32 v8, 0
	v_mov_b32_e32 v9, v28
	v_mov_b32_e32 v10, v28
	v_mov_b32_e32 v11, v28
	v_mov_b32_e32 v12, 0
	v_mov_b32_e32 v13, v28
	v_mov_b32_e32 v14, v28
	v_mov_b32_e32 v15, v28
	v_mov_b32_e32 v144, 0x3c000
	s_mov_b32 s59, s45
	v_lshl_add_u64 v[142:143], v[44:45], 0, s[58:59]
	v_mov_b64_e32 v[140:141], s[20:21]
	v_mad_u64_u32 v[140:141], s[10:11], v142, s90, v[140:141]
	v_mad_i32_i24 v141, v143, s90, v141
	s_lshl_b32 s44, s46, 1
	v_lshl_add_u64 v[140:141], v[140:141], 0, s[44:45]
	v_lshl_add_u64 v[140:141], v[140:141], 0, v[156:157]
	v_add_co_u32_e32 v142, vcc, s76, v140
	s_mov_b64 s[10:11], 0x1e200
	s_nop 0
	v_addc_co_u32_e32 v143, vcc, 0, v141, vcc
	global_load_dwordx4 v[120:123], v[142:143], off offset:512
	v_lshl_add_u64 v[142:143], v[140:141], 0, s[10:11]
	global_load_dwordx4 v[124:127], v[142:143], off offset:64
	global_load_dwordx4 v[128:131], v[140:141], off offset:512
	global_load_dwordx4 v[132:135], v[140:141], off offset:576
.LBB0_844:
	s_mov_b32 s59, s45
	v_lshl_add_u64 v[116:117], s[58:59], 1, v[46:47]
	s_waitcnt vmcnt(0)
	v_mfma_f32_16x16x32_bf16 v[24:27], v[120:123], v[16:19], 0
	v_mfma_f32_16x16x32_bf16 v[136:139], v[128:131], v[16:19], 0
	v_mfma_f32_16x16x32_bf16 v[24:27], v[124:127], v[20:23], v[24:27]
	v_mfma_f32_16x16x32_bf16 v[136:139], v[132:135], v[20:23], v[136:139]
	global_load_dwordx2 v[100:101], v[116:117], off
	global_load_dwordx2 v[102:103], v[116:117], off offset:32
	v_add_co_u32_e32 v118, vcc, s79, v116
	s_nop 1
	v_addc_co_u32_e32 v119, vcc, 0, v117, vcc
	global_load_dwordx2 v[104:105], v[118:119], off
	global_load_dwordx2 v[106:107], v[118:119], off offset:32
	v_add_co_u32_e32 v118, vcc, s91, v116
	s_nop 1
	v_addc_co_u32_e32 v119, vcc, 0, v117, vcc
	global_load_dwordx2 v[108:109], v[118:119], off
	global_load_dwordx2 v[110:111], v[118:119], off offset:32
	v_add_co_u32_e32 v118, vcc, s92, v116
	s_nop 1
	v_addc_co_u32_e32 v119, vcc, 0, v117, vcc
	global_load_dwordx2 v[112:113], v[118:119], off
	global_load_dwordx2 v[114:115], v[118:119], off offset:32
	v_sub_co_u32_e32 v140, vcc, v140, v144
	s_nop 1
	v_subbrev_co_u32_e32 v141, vcc, 0, v141, vcc
	v_add_co_u32_e32 v142, vcc, s76, v140
	s_mov_b64 s[10:11], 0x1e200
	s_nop 0
	v_addc_co_u32_e32 v143, vcc, 0, v141, vcc
	global_load_dwordx4 v[120:123], v[142:143], off offset:512
	v_lshl_add_u64 v[142:143], v[140:141], 0, s[10:11]
	global_load_dwordx4 v[124:127], v[142:143], off offset:64
	global_load_dwordx4 v[128:131], v[140:141], off offset:512
	global_load_dwordx4 v[132:135], v[140:141], off offset:576
	v_add_u32_e32 v29, s58, v36
	v_add_u32_e32 v30, 16, v29
	v_cmp_lt_u32_e32 vcc, v30, v33
	s_nop 7
	v_mul_f32_e32 v31, 0x3e000000, v24
	v_max_f32_e32 v30, 0, v31
	v_mul_f32_e64 v31, |v31|, s83
	v_exp_f32_e32 v31, v31
	s_nop 0
	v_add_f32_e32 v31, 1.0, v31
	v_cmp_gt_f32_e64 s[10:11], s93, v31
	s_nop 1
	v_cndmask_b32_e64 v52, 0, 32, s[10:11]
	v_ldexp_f32 v31, v31, v52
	v_log_f32_e32 v31, v31
	s_nop 0
	v_mul_f32_e32 v52, 0x3f317217, v31
	v_fma_f32 v52, v31, s96, -v52
	v_fmac_f32_e32 v52, 0x3377d1cf, v31
	v_fmac_f32_e32 v52, 0x3f317217, v31
	v_cmp_lt_f32_e64 s[12:13], |v31|, s77
	s_nop 1
	v_cndmask_b32_e64 v31, v31, v52, s[12:13]
	v_cndmask_b32_e64 v52, 0, v224, s[10:11]
	v_sub_f32_e32 v31, v31, v52
	v_add_f32_e32 v30, v30, v31
	v_cndmask_b32_e64 v31, 0, -v30, vcc
	v_fma_f32 v24, v24, s97, -v30
	v_mul_f32_e32 v30, 0x3e000000, v25
	v_add_u32_e32 v52, 17, v29
	v_cmp_lt_u32_e64 s[10:11], v52, v33
	v_max_f32_e32 v52, 0, v30
	v_mul_f32_e64 v30, |v30|, s83
	v_exp_f32_e32 v30, v30
	s_nop 0
	v_add_f32_e32 v30, 1.0, v30
	v_cmp_gt_f32_e64 s[12:13], s93, v30
	s_nop 1
	v_cndmask_b32_e64 v53, 0, 32, s[12:13]
	v_ldexp_f32 v30, v30, v53
	v_log_f32_e32 v30, v30
	s_nop 0
	v_mul_f32_e32 v53, 0x3f317217, v30
	v_fma_f32 v53, v30, s96, -v53
	v_fmac_f32_e32 v53, 0x3377d1cf, v30
	v_fmac_f32_e32 v53, 0x3f317217, v30
	v_cmp_lt_f32_e64 s[14:15], |v30|, s77
	s_nop 1
	v_cndmask_b32_e64 v30, v30, v53, s[14:15]
	v_cndmask_b32_e64 v53, 0, v224, s[12:13]
	v_sub_f32_e32 v30, v30, v53
	v_add_f32_e32 v30, v52, v30
	v_cndmask_b32_e64 v52, 0, -v30, s[10:11]
	v_fma_f32 v25, v25, s97, -v30
	v_mul_f32_e32 v30, 0x3e000000, v26
	v_add_u32_e32 v53, 18, v29
	v_cmp_lt_u32_e64 s[12:13], v53, v33
	v_max_f32_e32 v53, 0, v30
	v_mul_f32_e64 v30, |v30|, s83
	v_exp_f32_e32 v30, v30
	s_nop 0
	v_add_f32_e32 v30, 1.0, v30
	v_cmp_gt_f32_e64 s[14:15], s93, v30
	s_nop 1
	v_cndmask_b32_e64 v54, 0, 32, s[14:15]
	v_ldexp_f32 v30, v30, v54
	v_log_f32_e32 v30, v30
	s_nop 0
	v_mul_f32_e32 v54, 0x3f317217, v30
	v_fma_f32 v54, v30, s96, -v54
	v_fmac_f32_e32 v54, 0x3377d1cf, v30
	v_fmac_f32_e32 v54, 0x3f317217, v30
	v_cmp_lt_f32_e64 s[16:17], |v30|, s77
	s_nop 1
	v_cndmask_b32_e64 v30, v30, v54, s[16:17]
	v_cndmask_b32_e64 v54, 0, v224, s[14:15]
	v_sub_f32_e32 v30, v30, v54
	v_add_f32_e32 v30, v53, v30
	v_cndmask_b32_e64 v53, 0, -v30, s[12:13]
	v_fma_f32 v26, v26, s97, -v30
	v_mul_f32_e32 v30, 0x3e000000, v27
	v_add_u32_e32 v54, 19, v29
	v_cmp_lt_u32_e64 s[14:15], v54, v33
	v_max_f32_e32 v54, 0, v30
	v_mul_f32_e64 v30, |v30|, s83
	v_exp_f32_e32 v30, v30
	s_nop 0
	v_add_f32_e32 v30, 1.0, v30
	v_cmp_gt_f32_e64 s[16:17], s93, v30
	s_nop 1
	v_cndmask_b32_e64 v55, 0, 32, s[16:17]
	v_ldexp_f32 v30, v30, v55
	v_log_f32_e32 v30, v30
	s_nop 0
	v_mul_f32_e32 v55, 0x3f317217, v30
	v_fma_f32 v55, v30, s96, -v55
	v_fmac_f32_e32 v55, 0x3377d1cf, v30
	v_fmac_f32_e32 v55, 0x3f317217, v30
	v_cmp_lt_f32_e64 s[18:19], |v30|, s77
	s_nop 1
	v_cndmask_b32_e64 v30, v30, v55, s[18:19]
	v_cndmask_b32_e64 v55, 0, v224, s[16:17]
	v_sub_f32_e32 v30, v30, v55
	v_add_f32_e32 v30, v54, v30
	v_cndmask_b32_e64 v55, 0, -v30, s[14:15]
	v_add_f32_e32 v54, v55, v53
	v_add_f32_e32 v52, v52, v54
	v_fma_f32 v27, v27, s97, -v30
	v_add_f32_e32 v30, v31, v52
	ds_bpermute_b32 v31, v35, v30
	ds_bpermute_b32 v53, v37, v30
	ds_bpermute_b32 v56, v50, v30
	s_waitcnt lgkmcnt(2)
	v_cndmask_b32_e64 v31, v31, 0, s[4:5]
	s_waitcnt lgkmcnt(1)
	v_cndmask_b32_e64 v53, 0, v53, s[6:7]
	v_add_f32_e32 v31, v31, v53
	s_waitcnt lgkmcnt(0)
	v_cndmask_b32_e64 v53, 0, v56, s[8:9]
	v_add_f32_e32 v31, v31, v53
	v_add_f32_e32 v30, v31, v30
	v_add_f32_e32 v31, v28, v31
	v_add_f32_e32 v24, v31, v24
	v_add_f32_e32 v24, v24, v52
	v_mul_f32_e32 v24, 0x3fb8aa3b, v24
	v_exp_f32_e32 v24, v24
	ds_bpermute_b32 v30, v51, v30
	v_cndmask_b32_e32 v53, 0, v24, vcc
	v_add_f32_e32 v24, v31, v25
	v_add_f32_e32 v24, v54, v24
	v_mul_f32_e32 v24, 0x3fb8aa3b, v24
	v_exp_f32_e32 v24, v24
	v_cmp_lt_u32_e32 vcc, v29, v33
	v_cndmask_b32_e64 v54, 0, v24, s[10:11]
	v_add_f32_e32 v24, v31, v26
	v_add_f32_e32 v24, v55, v24
	v_mul_f32_e32 v24, 0x3fb8aa3b, v24
	v_exp_f32_e32 v24, v24
	s_nop 0
	v_cndmask_b32_e64 v55, 0, v24, s[12:13]
	v_add_f32_e32 v24, v31, v27
	v_mul_f32_e32 v24, 0x3fb8aa3b, v24
	v_exp_f32_e32 v24, v24
	s_nop 0
	v_cndmask_b32_e64 v56, 0, v24, s[14:15]
	v_mov_b32_e32 v24, v136
	v_mov_b32_e32 v25, v137
	v_mov_b32_e32 v26, v138
	v_mov_b32_e32 v27, v139
	v_mul_f32_e32 v31, 0x3e000000, v24
	v_max_f32_e32 v48, 0, v31
	v_mul_f32_e64 v31, |v31|, s83
	v_exp_f32_e32 v31, v31
	s_nop 0
	v_add_f32_e32 v31, 1.0, v31
	v_cmp_gt_f32_e64 s[10:11], s93, v31
	s_nop 1
	v_cndmask_b32_e64 v49, 0, 32, s[10:11]
	v_ldexp_f32 v31, v31, v49
	v_log_f32_e32 v31, v31
	s_nop 0
	v_mul_f32_e32 v49, 0x3f317217, v31
	v_fma_f32 v49, v31, s96, -v49
	v_fmac_f32_e32 v49, 0x3377d1cf, v31
	v_fmac_f32_e32 v49, 0x3f317217, v31
	v_cmp_lt_f32_e64 s[12:13], |v31|, s77
	s_nop 1
	v_cndmask_b32_e64 v31, v31, v49, s[12:13]
	v_cndmask_b32_e64 v49, 0, v224, s[10:11]
	v_sub_f32_e32 v31, v31, v49
	v_add_f32_e32 v48, v48, v31
	v_cndmask_b32_e64 v31, 0, -v48, vcc
	v_fma_f32 v24, v24, s97, -v48
	v_mul_f32_e32 v48, 0x3e000000, v25
	v_add_u32_e32 v49, 1, v29
	v_cmp_lt_u32_e64 s[10:11], v49, v33
	v_max_f32_e32 v49, 0, v48
	v_mul_f32_e64 v48, |v48|, s83
	v_exp_f32_e32 v48, v48
	s_nop 0
	v_add_f32_e32 v48, 1.0, v48
	v_cmp_gt_f32_e64 s[12:13], s93, v48
	s_nop 1
	v_cndmask_b32_e64 v52, 0, 32, s[12:13]
	v_ldexp_f32 v48, v48, v52
	v_log_f32_e32 v48, v48
	s_nop 0
	v_mul_f32_e32 v52, 0x3f317217, v48
	v_fma_f32 v52, v48, s96, -v52
	v_fmac_f32_e32 v52, 0x3377d1cf, v48
	v_fmac_f32_e32 v52, 0x3f317217, v48
	v_cmp_lt_f32_e64 s[14:15], |v48|, s77
	s_nop 1
	v_cndmask_b32_e64 v48, v48, v52, s[14:15]
	v_cndmask_b32_e64 v52, 0, v224, s[12:13]
	v_sub_f32_e32 v48, v48, v52
	v_add_f32_e32 v48, v49, v48
	v_cndmask_b32_e64 v49, 0, -v48, s[10:11]
	v_fma_f32 v25, v25, s97, -v48
	v_mul_f32_e32 v48, 0x3e000000, v26
	v_add_u32_e32 v52, 2, v29
	v_cmp_lt_u32_e64 s[12:13], v52, v33
	v_max_f32_e32 v52, 0, v48
	v_mul_f32_e64 v48, |v48|, s83
	v_exp_f32_e32 v48, v48
	v_add_u32_e32 v29, 3, v29
	v_add_f32_e32 v48, 1.0, v48
	v_cmp_gt_f32_e64 s[14:15], s93, v48
	s_nop 1
	v_cndmask_b32_e64 v57, 0, 32, s[14:15]
	v_ldexp_f32 v48, v48, v57
	v_log_f32_e32 v48, v48
	s_nop 0
	v_mul_f32_e32 v57, 0x3f317217, v48
	v_fma_f32 v57, v48, s96, -v57
	v_fmac_f32_e32 v57, 0x3377d1cf, v48
	v_fmac_f32_e32 v57, 0x3f317217, v48
	v_cmp_lt_f32_e64 s[16:17], |v48|, s77
	s_nop 1
	v_cndmask_b32_e64 v48, v48, v57, s[16:17]
	v_cndmask_b32_e64 v57, 0, v224, s[14:15]
	v_sub_f32_e32 v48, v48, v57
	v_add_f32_e32 v48, v52, v48
	v_cndmask_b32_e64 v52, 0, -v48, s[12:13]
	v_fma_f32 v26, v26, s97, -v48
	v_mul_f32_e32 v48, 0x3e000000, v27
	v_cmp_lt_u32_e64 s[14:15], v29, v33
	v_max_f32_e32 v29, 0, v48
	v_mul_f32_e64 v48, |v48|, s83
	v_exp_f32_e32 v48, v48
	s_nop 0
	v_add_f32_e32 v48, 1.0, v48
	v_cmp_gt_f32_e64 s[16:17], s93, v48
	s_nop 1
	v_cndmask_b32_e64 v57, 0, 32, s[16:17]
	v_ldexp_f32 v48, v48, v57
	v_log_f32_e32 v48, v48
	s_nop 0
	v_mul_f32_e32 v57, 0x3f317217, v48
	v_fma_f32 v57, v48, s96, -v57
	v_fmac_f32_e32 v57, 0x3377d1cf, v48
	v_fmac_f32_e32 v57, 0x3f317217, v48
	v_cmp_lt_f32_e64 s[18:19], |v48|, s77
	s_nop 1
	v_cndmask_b32_e64 v48, v48, v57, s[18:19]
	v_cndmask_b32_e64 v57, 0, v224, s[16:17]
	v_sub_f32_e32 v48, v48, v57
	v_add_f32_e32 v29, v29, v48
	v_cndmask_b32_e64 v57, 0, -v29, s[14:15]
	v_add_f32_e32 v58, v57, v52
	v_add_f32_e32 v59, v49, v58
	v_add_f32_e32 v52, v31, v59
	v_fma_f32 v27, v27, s97, -v29
	ds_bpermute_b32 v29, v35, v52
	ds_bpermute_b32 v31, v37, v52
	ds_bpermute_b32 v48, v50, v52
	s_waitcnt lgkmcnt(2)
	v_cndmask_b32_e64 v29, v29, 0, s[4:5]
	s_waitcnt lgkmcnt(1)
	v_cndmask_b32_e64 v31, 0, v31, s[6:7]
	v_add_f32_e32 v29, v29, v31
	s_waitcnt lgkmcnt(0)
	v_cndmask_b32_e64 v31, 0, v48, s[8:9]
	v_pk_add_f32 v[48:49], v[28:29], v[30:31]
	s_nop 0
	v_add_f32_e32 v28, v49, v52
	ds_bpermute_b32 v52, v51, v28
	v_add_f32_e32 v28, v48, v49
	v_add_f32_e32 v24, v28, v24
	v_add_f32_e32 v25, v28, v25
	v_add_f32_e32 v26, v28, v26
	v_add_f32_e32 v24, v24, v59
	v_add_f32_e32 v25, v58, v25
	v_add_f32_e32 v26, v57, v26
	v_add_f32_e32 v27, v28, v27
	v_mul_f32_e32 v24, 0x3fb8aa3b, v24
	v_mul_f32_e32 v25, 0x3fb8aa3b, v25
	v_mul_f32_e32 v26, 0x3fb8aa3b, v26
	v_mul_f32_e32 v27, 0x3fb8aa3b, v27
	v_exp_f32_e32 v24, v24
	v_exp_f32_e32 v25, v25
	v_exp_f32_e32 v26, v26
	v_exp_f32_e32 v27, v27
	v_cndmask_b32_e32 v24, 0, v24, vcc
	v_cndmask_b32_e64 v25, 0, v25, s[10:11]
	v_cndmask_b32_e64 v26, 0, v26, s[12:13]
	v_cndmask_b32_e64 v27, 0, v27, s[14:15]
	v_cvt_pk_bf16_f32 v24, v24, v25
	v_cvt_pk_bf16_f32 v25, v26, v27
	v_cvt_pk_bf16_f32 v26, v53, v54
	v_cvt_pk_bf16_f32 v27, v55, v56
	s_mov_b32 s10, 0xc2b40000
	s_nop 1
	s_waitcnt vmcnt(10)
	v_mfma_f32_16x16x32_bf16 v[12:15], v[100:103], v[24:27], v[12:15]
	s_waitcnt vmcnt(8)
	v_mfma_f32_16x16x32_bf16 v[8:11], v[104:107], v[24:27], v[8:11]
	s_waitcnt vmcnt(6)
	v_mfma_f32_16x16x32_bf16 v[4:7], v[108:111], v[24:27], v[4:7]
	s_waitcnt vmcnt(4)
	v_mfma_f32_16x16x32_bf16 v[0:3], v[112:115], v[24:27], v[0:3]
	s_waitcnt lgkmcnt(0)
	v_add_f32_e32 v28, v48, v52
	v_cmp_gt_f32_e32 vcc, s10, v28
	s_cmp_lg_u64 vcc, exec
	s_cselect_b64 s[10:11], -1, 0
	s_cmp_lg_u32 s58, 0
	s_cselect_b64 s[12:13], -1, 0
	s_and_b64 s[10:11], s[12:13], s[10:11]
	s_sub_i32 s58, s58, 32
	s_and_b64 vcc, exec, s[10:11]
	s_cbranch_vccnz .LBB0_844
	v_pk_mul_f32 v[16:17], v[14:15], v[14:15]
	v_pk_mul_f32 v[18:19], v[12:13], v[12:13]
	v_lshlrev_b32_e32 v156, 1, v36
	v_pk_mov_b32 v[20:21], v[18:19], v[16:17] op_sel:[1,0]
	v_mov_b32_e32 v19, v17
	v_pk_add_f32 v[16:17], v[20:21], v[18:19]
	v_pk_mul_f32 v[18:19], v[10:11], v[10:11]
	v_pk_mul_f32 v[20:21], v[8:9], v[8:9]
	v_pk_add_f32 v[16:17], v[16:17], v[16:17] op_sel:[0,1] op_sel_hi:[1,0]
	v_pk_mov_b32 v[22:23], v[20:21], v[18:19] op_sel:[1,0]
	v_mov_b32_e32 v21, v19
	v_pk_add_f32 v[18:19], v[22:23], v[20:21]
	v_mul_f32_e32 v20, v0, v0
	v_mul_f32_e32 v21, v1, v1
	v_pk_add_f32 v[18:19], v[18:19], v[18:19] op_sel:[0,1] op_sel_hi:[1,0]
	v_mov_b32_e32 v17, v20
	v_mov_b32_e32 v19, v21
	v_pk_add_f32 v[16:17], v[16:17], v[18:19]
	v_mul_f32_e32 v18, v5, v5
	v_mul_f32_e32 v20, v7, v7
	v_mul_f32_e32 v22, v2, v2
	v_mul_f32_e32 v23, v3, v3
	v_pk_fma_f32 v[18:19], v[4:5], v[4:5], v[18:19] op_sel_hi:[1,1,0]
	v_pk_fma_f32 v[20:21], v[6:7], v[6:7], v[20:21] op_sel_hi:[1,1,0]
	v_mov_b32_e32 v19, v22
	v_mov_b32_e32 v21, v23
	v_pk_add_f32 v[18:19], v[18:19], v[20:21]
	v_pk_add_f32 v[16:17], v[16:17], v[18:19]
	v_and_b32_e32 v18, 64, v217
	v_add_f32_e32 v16, v16, v17
	v_xor_b32_e32 v17, 16, v217
	v_add_u32_e32 v18, 64, v18
	v_cmp_lt_i32_e32 vcc, v17, v18
	s_mov_b64 s[10:11], 0
	s_nop 0
	v_cndmask_b32_e32 v17, v217, v17, vcc
	v_lshlrev_b32_e32 v17, 2, v17
	ds_bpermute_b32 v17, v17, v16
	s_waitcnt lgkmcnt(0)
	v_add_f32_e32 v16, v16, v17
	v_xor_b32_e32 v17, 32, v217
	v_cmp_lt_i32_e32 vcc, v17, v18
	s_nop 1
	v_cndmask_b32_e32 v17, v217, v17, vcc
	v_lshlrev_b32_e32 v17, 2, v17
	ds_bpermute_b32 v17, v17, v16
	s_waitcnt lgkmcnt(0)
	v_add_f32_e32 v16, v16, v17
	v_fmamk_f32 v16, v16, 0x3c800000, v212
	v_rsq_f32_e32 v18, v16
	v_lshlrev_b64 v[16:17], 11, v[42:43]
	v_lshl_add_u64 v[16:17], s[36:37], 0, v[16:17]
	v_lshl_add_u64 v[16:17], v[16:17], 0, s[44:45]
	v_pk_mul_f32 v[12:13], v[12:13], v[18:19] op_sel_hi:[1,0]
	v_pk_mul_f32 v[14:15], v[14:15], v[18:19] op_sel_hi:[1,0]
	v_lshl_add_u64 v[16:17], v[16:17], 0, v[156:157]
	v_pk_mul_f32 v[8:9], v[8:9], v[18:19] op_sel_hi:[1,0]
	v_pk_mul_f32 v[10:11], v[10:11], v[18:19] op_sel_hi:[1,0]
	v_pk_mul_f32 v[4:5], v[4:5], v[18:19] op_sel_hi:[1,0]
	v_pk_mul_f32 v[6:7], v[6:7], v[18:19] op_sel_hi:[1,0]
	v_pk_mul_f32 v[0:1], v[0:1], v[18:19] op_sel_hi:[1,0]
	v_pk_mul_f32 v[2:3], v[2:3], v[18:19] op_sel_hi:[1,0]
	v_pk_mul_f32 v[12:13], v[64:65], v[12:13]
	v_pk_mul_f32 v[14:15], v[66:67], v[14:15]
	v_cvt_pk_bf16_f32 v12, v12, v13
	v_cvt_pk_bf16_f32 v13, v14, v15
	global_store_dwordx2 v[16:17], v[12:13], off
	v_pk_mul_f32 v[8:9], v[68:69], v[8:9]
	v_pk_mul_f32 v[10:11], v[70:71], v[10:11]
	v_cvt_pk_bf16_f32 v8, v8, v9
	v_cvt_pk_bf16_f32 v9, v10, v11
	global_store_dwordx2 v[16:17], v[8:9], off offset:32
	v_pk_mul_f32 v[4:5], v[4:5], v[72:73]
	v_pk_mul_f32 v[6:7], v[6:7], v[74:75]
	v_cvt_pk_bf16_f32 v4, v4, v5
	v_cvt_pk_bf16_f32 v5, v6, v7
	global_store_dwordx2 v[16:17], v[4:5], off offset:64
	v_pk_mul_f32 v[0:1], v[0:1], v[76:77]
	v_pk_mul_f32 v[2:3], v[2:3], v[78:79]
	v_cvt_pk_bf16_f32 v0, v0, v1
	v_cvt_pk_bf16_f32 v1, v2, v3
	global_store_dwordx2 v[16:17], v[0:1], off offset:96
	s_branch .LBB0_837
